# GEMM phase prologues: K-tile 1's six LDS-DMA pieces issued together with K-tile 0's (first wait vmcnt(8) next to the second) instead of one memory latency later
# baseline (speedup 1.0000x reference)
; #define PG8_STAGE(bufoff, gbase, voff) do { _Pragma("unroll") for (int _i = 0; _i < 2; ++_i) \
;         __builtin_amdgcn_global_load_lds((const unsigned*)((const char*)(gbase) + (voff)[_i]), (PG8_LAS unsigned*)(lds + (bufoff) + ldsw + _i * 8192), 16, 0, 0); } while (0)
; #define PG8_WAIT_V(n) asm volatile("s_waitcnt vmcnt(" #n ")" ::: "memory")
; #define PG8_BAR __builtin_amdgcn_s_barrier()
; template <class Epi, class Sched, bool ALIGN_EPI = false, bool SP2 = false>
; __device__ __forceinline__ void gemm_phase(PG8_LAS unsigned char* lds, const Gemm g, const Sched& S, const Epi& E) {
;     ...
;     for (int i = 0; i < 2; ++i) { int R, C; stage_rc(tid * 16 + i * 8192, R, C); const int Rb = Epi::PERM ? ((R & ~31) + perm32(R & 31)) : R;
;         voffA[i] = (unsigned)(R * K + C) * 2u; voffB[i] = (unsigned)(Rb * K + C) * 2u; }
;     const size_t kstep = (size_t)(BK * 2);
;     const size_t hstep = (size_t)HALF * K * 2;
;     const size_t tstep = 2 * hstep;
;     const unsigned ldsw = (unsigned)wid * 1024u;
;     const int aoff = lds_byte(wr * 64 + fr, fq * 8), boff = lds_byte(wc * 32 + fr, fq * 8);
;     ...
;         PG8_STAGE(PG8_SB(1, 0), cB + kstep, voffB); PG8_STAGE(PG8_SA(1, 0), cA + kstep, voffA); PG8_STAGE(PG8_SB(1, 1), cB + hstep + kstep, voffB);
;         PG8_WAIT_V(6); PG8_BAR;
.LBB0_238:
	v_readlane_b32 s18, v255, 6
	v_mov_b32_e32 v155, v145
	v_readlane_b32 s19, v255, 7
	v_mov_b32_e32 v151, v145
	v_readlane_b32 s16, v253, 17
	v_lshl_add_u64 v[8:9], s[18:19], 0, v[154:155]
	v_lshl_add_u64 v[10:11], s[18:19], 0, v[150:151]
	v_mov_b32_e32 v157, v145
	v_readlane_b32 s17, v253, 18
	s_add_i32 m0, s25, 0x18000
	v_lshl_add_u64 v[8:9], v[8:9], 0, s[94:95]
	v_lshl_add_u64 v[12:13], s[16:17], 0, v[156:157]
	v_mov_b32_e32 v153, v145
	global_load_lds_dwordx4 v[8:9], off
	v_lshl_add_u64 v[8:9], v[10:11], 0, s[94:95]
	s_add_i32 m0, s25, 0x1a000
	s_add_i32 s29, s25, 0x8000
	v_lshl_add_u64 v[14:15], s[16:17], 0, v[152:153]
	global_load_lds_dwordx4 v[8:9], off
	v_lshl_add_u64 v[8:9], v[12:13], 0, s[94:95]
	s_mov_b32 m0, s29
	s_add_i32 s30, s25, 0xa000
	v_readlane_b32 s6, v255, 8
	global_load_lds_dwordx4 v[8:9], off
	v_lshl_add_u64 v[8:9], v[14:15], 0, s[94:95]
	s_mov_b32 m0, s30
	v_readlane_b32 s7, v255, 9
	global_load_lds_dwordx4 v[8:9], off
	s_add_i32 m0, s25, 0x1c000
	v_lshl_add_u64 v[8:9], s[6:7], 0, v[154:155]
	global_load_lds_dwordx4 v[8:9], off
	v_lshl_add_u64 v[8:9], s[6:7], 0, v[150:151]
	s_add_i32 m0, s25, 0x1e000
	v_and_b32_e32 v10, 48, v2
	global_load_lds_dwordx4 v[8:9], off
	v_and_b32_e32 v8, 15, v2
	v_lshl_or_b32 v159, s4, 6, v8
	v_lshrrev_b32_e32 v9, 1, v2
	v_and_b32_e32 v158, 24, v9
	v_lshlrev_b32_e32 v9, 6, v159
	s_movk_i32 s6, 0x3c0
	v_lshlrev_b32_e32 v12, 2, v2
	s_and_b32 s5, s0, 3
	v_and_or_b32 v11, v9, s6, v10
	s_lshl_b32 s4, s4, 13
	v_and_b32_e32 v12, 32, v12
	s_waitcnt vmcnt(8)
	s_barrier
	s_waitcnt vmcnt(6)
	v_bitop3_b32 v11, v11, s4, v12 bitop3:0xde
	v_lshl_or_b32 v8, v8, 6, v10
	s_lshl_b32 s4, s5, 12
	s_lshl_b32 s31, s5, 5
	v_bitop3_b32 v197, v8, s4, v12 bitop3:0xde
	s_barrier
	v_lshlrev_b32_e32 v8, 14, v6
	v_and_b32_e32 v8, 0xffff8000, v8
	s_lshl_b32 s4, s0, 11
	v_lshl_add_u32 v5, v5, 11, v8
	v_and_b32_e32 v6, 1, v6
	v_bfe_u32 v2, v2, 2, 4
	s_cmpk_lt_u32 s1, 0x100
	v_lshl_or_b32 v5, v6, 6, v5
	v_lshl_or_b32 v198, s0, 5, v2
	s_cselect_b64 s[42:43], -1, 0
	v_and_or_b32 v2, s31, 32, v158
	s_lshl_b32 s0, s0, 6
	v_and_b32_e32 v144, 48, v3
	v_readlane_b32 s6, v251, 27
	v_lshl_add_u32 v166, v7, 1, v5
	v_lshlrev_b32_e32 v5, 14, v0
	s_and_b32 s0, s0, 0x80
	v_lshl_add_u64 v[160:161], s[92:93], 0, v[144:145]
	v_readlane_b32 s1, v253, 45
	v_lshlrev_b32_e32 v144, 2, v2
	v_readlane_b32 s7, v251, 28
	v_and_b32_e32 v5, 0xffff8000, v5
	v_add_u32_e32 v3, s1, v10
	v_lshl_add_u64 v[162:163], s[6:7], 0, v[144:145]
	v_readlane_b32 s6, v251, 29
	v_lshl_add_u32 v1, v1, 11, v5
	v_and_b32_e32 v0, 1, v0
	s_lshl_b32 s44, s0, 1
	v_readlane_b32 s0, v253, 15
	v_readlane_b32 s7, v251, 30
	v_lshl_or_b32 v0, v0, 6, v1
	s_add_i32 s35, s4, 0
	v_readlane_b32 s1, v253, 16
	v_lshl_add_u64 v[164:165], s[6:7], 0, v[144:145]
	v_mov_b32_e32 v167, v145
	v_lshl_add_u32 v168, v4, 1, v0
	v_mov_b32_e32 v169, v145
	s_mov_b32 s34, 0
	s_add_i32 s54, s35, 0x20400
	v_add_u32_e32 v199, 0, v11
	v_add_u32_e32 v200, v3, v9
	v_lshlrev_b32_e32 v170, 1, v2
	s_mov_b32 s56, s0
	v_readlane_b32 s45, v253, 4
	s_mov_b64 s[0:1], s[18:19]
	s_mov_b64 s[4:5], s[16:17]
	s_branch .LBB0_241

; #define PG8_STAGE(bufoff, gbase, voff) do { _Pragma("unroll") for (int _i = 0; _i < 2; ++_i) \
;         __builtin_amdgcn_global_load_lds((const unsigned*)((const char*)(gbase) + (voff)[_i]), (PG8_LAS unsigned*)(lds + (bufoff) + ldsw + _i * 8192), 16, 0, 0); } while (0)
; #define PG8_WAIT_V(n) asm volatile("s_waitcnt vmcnt(" #n ")" ::: "memory")
; #define PG8_BAR __builtin_amdgcn_s_barrier()
; template <class Epi, class Sched, bool ALIGN_EPI = false, bool SP2 = false>
; __device__ __forceinline__ void gemm_phase(PG8_LAS unsigned char* lds, const Gemm g, const Sched& S, const Epi& E) {
;     ...
;         PG8_STAGE(PG8_SB(1, 0), cB + kstep, voffB); PG8_STAGE(PG8_SA(1, 0), cA + kstep, voffA); PG8_STAGE(PG8_SB(1, 1), cB + hstep + kstep, voffB);
;         PG8_WAIT_V(6); PG8_BAR;
;     __device__ __forceinline__ void finish(f32x4 (&acc)[2][2][4][2], const Pre& p) const {
; #pragma unroll
;         for (int ai = 0; ai < 2; ++ai)
; #pragma unroll
;             for (int m = 0; m < 4; ++m)
; #pragma unroll
;                 for (int bj = 0; bj < 2; ++bj) { float f[8]; unpack8(p.v[ai][m][bj], f);
;                     acc[ai][bj][m][0] = (f32x4){f[0], f[1], f[2], f[3]} * inv_alpha; acc[ai][bj][m][1] = (f32x4){f[4], f[5], f[6], f[7]} * inv_alpha; }
;     }
.LBB0_1552:
	v_or_b32_e32 v142, s5, v64
	v_lshlrev_b32_e32 v65, 6, v142
	v_lshlrev_b32_e32 v74, 4, v134
	s_movk_i32 s5, 0x3c0
	v_lshlrev_b32_e32 v75, 2, v142
	v_readlane_b32 s6, v255, 14
	v_and_or_b32 v65, v65, s5, v74
	s_lshl_b32 s4, s4, 13
	v_and_b32_e32 v75, 32, v75
	v_readlane_b32 s7, v255, 15
	v_bitop3_b32 v151, v65, s4, v75 bitop3:0xde
	v_lshl_or_b32 v65, v64, 6, v74
	v_lshlrev_b32_e32 v64, 2, v64
	v_lshl_add_u64 v[66:67], s[6:7], 0, v[144:145]
	v_mov_b32_e32 v129, v145
	v_readlane_b32 s28, v253, 26
	s_lshl_b32 s4, s24, 12
	v_and_b32_e32 v64, 32, v64
	v_lshl_add_u64 v[68:69], s[6:7], 0, v[128:129]
	v_mov_b32_e32 v133, v145
	v_readlane_b32 s29, v253, 27
	v_bitop3_b32 v143, v65, s4, v64 bitop3:0xde
	s_add_i32 m0, s26, 0x18000
	v_lshl_add_u64 v[64:65], v[66:67], 0, s[94:95]
	v_lshl_add_u64 v[70:71], s[28:29], 0, v[132:133]
	v_mov_b32_e32 v131, v145
	global_load_lds_dwordx4 v[64:65], off
	v_lshl_add_u64 v[64:65], v[68:69], 0, s[94:95]
	s_add_i32 m0, s26, 0x1a000
	s_add_i32 s34, s26, 0x8000
	v_lshl_add_u64 v[72:73], s[28:29], 0, v[130:131]
	global_load_lds_dwordx4 v[64:65], off
	v_lshl_add_u64 v[64:65], v[70:71], 0, s[94:95]
	s_mov_b32 m0, s34
	s_add_i32 s35, s26, 0xa000
	v_readlane_b32 s4, v255, 16
	global_load_lds_dwordx4 v[64:65], off
	v_lshl_add_u64 v[64:65], v[72:73], 0, s[94:95]
	s_mov_b32 m0, s35
	v_readlane_b32 s5, v255, 17
	global_load_lds_dwordx4 v[64:65], off
	s_add_i32 m0, s26, 0x1c000
	v_lshl_add_u64 v[64:65], s[4:5], 0, v[144:145]
	global_load_lds_dwordx4 v[64:65], off
	v_lshl_add_u64 v[64:65], s[4:5], 0, v[128:129]
	s_add_i32 m0, s26, 0x1e000
	s_nop 0
	global_load_lds_dwordx4 v[64:65], off
	s_waitcnt vmcnt(8)
	s_barrier
	s_waitcnt vmcnt(6)
	s_barrier
	s_waitcnt vmcnt(0)
	v_lshlrev_b32_e32 v120, 16, v60
	v_and_b32_e32 v121, 0xffff0000, v60
	v_lshlrev_b32_e32 v122, 16, v61
	v_and_b32_e32 v123, 0xffff0000, v61
	v_lshlrev_b32_e32 v124, 16, v62
	v_and_b32_e32 v125, 0xffff0000, v62
	v_lshlrev_b32_e32 v126, 16, v63
	v_and_b32_e32 v127, 0xffff0000, v63
	v_lshlrev_b32_e32 v112, 16, v56
	v_and_b32_e32 v113, 0xffff0000, v56
	v_lshlrev_b32_e32 v114, 16, v57
	v_and_b32_e32 v115, 0xffff0000, v57
	v_lshlrev_b32_e32 v116, 16, v58
	v_and_b32_e32 v117, 0xffff0000, v58
	v_lshlrev_b32_e32 v118, 16, v59
	v_and_b32_e32 v119, 0xffff0000, v59
	v_lshlrev_b32_e32 v100, 16, v52
	v_and_b32_e32 v101, 0xffff0000, v52
	v_lshlrev_b32_e32 v102, 16, v53
	v_and_b32_e32 v103, 0xffff0000, v53
	v_lshlrev_b32_e32 v104, 16, v54
	v_and_b32_e32 v105, 0xffff0000, v54
	v_lshlrev_b32_e32 v106, 16, v55
	v_and_b32_e32 v107, 0xffff0000, v55
	v_lshlrev_b32_e32 v96, 16, v48
	v_and_b32_e32 v97, 0xffff0000, v48
	v_lshlrev_b32_e32 v98, 16, v49
	v_and_b32_e32 v99, 0xffff0000, v49
	v_lshlrev_b32_e32 v108, 16, v50
	v_and_b32_e32 v109, 0xffff0000, v50
	v_lshlrev_b32_e32 v110, 16, v51
	v_and_b32_e32 v111, 0xffff0000, v51
	v_lshlrev_b32_e32 v84, 16, v44
	v_and_b32_e32 v85, 0xffff0000, v44
	v_lshlrev_b32_e32 v86, 16, v45
	v_and_b32_e32 v87, 0xffff0000, v45
	v_lshlrev_b32_e32 v88, 16, v46
	v_and_b32_e32 v89, 0xffff0000, v46
	v_lshlrev_b32_e32 v90, 16, v47
	v_and_b32_e32 v91, 0xffff0000, v47
	v_lshlrev_b32_e32 v80, 16, v40
	v_and_b32_e32 v81, 0xffff0000, v40
	v_lshlrev_b32_e32 v82, 16, v41
	v_and_b32_e32 v83, 0xffff0000, v41
	v_lshlrev_b32_e32 v92, 16, v42
	v_and_b32_e32 v93, 0xffff0000, v42
	v_lshlrev_b32_e32 v94, 16, v43
	v_and_b32_e32 v95, 0xffff0000, v43
	v_lshlrev_b32_e32 v68, 16, v36
	v_and_b32_e32 v69, 0xffff0000, v36
	v_lshlrev_b32_e32 v70, 16, v37
	v_and_b32_e32 v71, 0xffff0000, v37
	v_lshlrev_b32_e32 v72, 16, v38
	v_and_b32_e32 v73, 0xffff0000, v38
	v_lshlrev_b32_e32 v74, 16, v39
	v_and_b32_e32 v75, 0xffff0000, v39
	v_lshlrev_b32_e32 v64, 16, v28
	v_and_b32_e32 v65, 0xffff0000, v28
	v_lshlrev_b32_e32 v66, 16, v29
	v_and_b32_e32 v67, 0xffff0000, v29
	v_lshlrev_b32_e32 v76, 16, v30
	v_and_b32_e32 v77, 0xffff0000, v30
	v_lshlrev_b32_e32 v78, 16, v31
	v_and_b32_e32 v79, 0xffff0000, v31
	v_lshlrev_b32_e32 v52, 16, v32
	v_and_b32_e32 v53, 0xffff0000, v32
	v_lshlrev_b32_e32 v54, 16, v33
	v_and_b32_e32 v55, 0xffff0000, v33
	v_lshlrev_b32_e32 v56, 16, v34
	v_and_b32_e32 v57, 0xffff0000, v34
	v_lshlrev_b32_e32 v58, 16, v35
	v_and_b32_e32 v59, 0xffff0000, v35
	v_lshlrev_b32_e32 v48, 16, v20
	v_and_b32_e32 v49, 0xffff0000, v20
	v_lshlrev_b32_e32 v50, 16, v21
	v_and_b32_e32 v51, 0xffff0000, v21
	v_lshlrev_b32_e32 v60, 16, v22
	v_and_b32_e32 v61, 0xffff0000, v22
	v_lshlrev_b32_e32 v62, 16, v23
	v_and_b32_e32 v63, 0xffff0000, v23
	v_lshlrev_b32_e32 v36, 16, v24
	v_and_b32_e32 v37, 0xffff0000, v24
	v_lshlrev_b32_e32 v38, 16, v25
	v_and_b32_e32 v39, 0xffff0000, v25
	v_lshlrev_b32_e32 v40, 16, v26
	v_and_b32_e32 v41, 0xffff0000, v26
	v_lshlrev_b32_e32 v42, 16, v27
	v_and_b32_e32 v43, 0xffff0000, v27
	v_lshlrev_b32_e32 v32, 16, v4
	v_and_b32_e32 v33, 0xffff0000, v4
	v_lshlrev_b32_e32 v34, 16, v5
	v_and_b32_e32 v35, 0xffff0000, v5
	v_lshlrev_b32_e32 v44, 16, v6
	v_and_b32_e32 v45, 0xffff0000, v6
	v_lshlrev_b32_e32 v46, 16, v7
	v_and_b32_e32 v47, 0xffff0000, v7
	v_lshlrev_b32_e32 v20, 16, v16
	v_and_b32_e32 v21, 0xffff0000, v16
	v_lshlrev_b32_e32 v22, 16, v17
	v_and_b32_e32 v23, 0xffff0000, v17
	v_lshlrev_b32_e32 v24, 16, v18
	v_and_b32_e32 v25, 0xffff0000, v18
	v_lshlrev_b32_e32 v26, 16, v19
	v_and_b32_e32 v27, 0xffff0000, v19
	v_lshlrev_b32_e32 v16, 16, v0
	v_and_b32_e32 v17, 0xffff0000, v0
	v_lshlrev_b32_e32 v18, 16, v1
	v_and_b32_e32 v19, 0xffff0000, v1
	v_lshlrev_b32_e32 v28, 16, v2
	v_and_b32_e32 v29, 0xffff0000, v2
	v_lshlrev_b32_e32 v30, 16, v3
	v_and_b32_e32 v31, 0xffff0000, v3
	v_lshlrev_b32_e32 v4, 16, v8
	v_and_b32_e32 v5, 0xffff0000, v8
	v_lshlrev_b32_e32 v6, 16, v9
	v_and_b32_e32 v7, 0xffff0000, v9
	v_lshlrev_b32_e32 v8, 16, v10
	v_and_b32_e32 v9, 0xffff0000, v10
	v_lshlrev_b32_e32 v10, 16, v11
	v_and_b32_e32 v11, 0xffff0000, v11
	v_lshlrev_b32_e32 v0, 16, v12
	v_and_b32_e32 v1, 0xffff0000, v12
	v_lshlrev_b32_e32 v2, 16, v13
	v_and_b32_e32 v3, 0xffff0000, v13
	v_lshlrev_b32_e32 v12, 16, v14
	v_and_b32_e32 v13, 0xffff0000, v14
	v_lshlrev_b32_e32 v14, 16, v15
	v_and_b32_e32 v15, 0xffff0000, v15
	v_cmp_eq_u32_e64 s[36:37], 0, v134
	v_lshlrev_b32_e32 v134, 14, v140
	v_and_b32_e32 v134, 0xffff8000, v134
	v_lshl_add_u32 v134, v139, 11, v134
	v_lshlrev_b32_e32 v139, 14, v136
	v_and_b32_e32 v139, 0xffff8000, v139
	v_or_b32_e32 v150, s1, v135
	v_and_b32_e32 v135, 1, v140
	v_lshl_add_u32 v137, v137, 11, v139
	v_and_b32_e32 v136, 1, v136
	s_cmpk_lt_u32 s0, 0x100
	v_lshl_or_b32 v134, v135, 6, v134
	v_lshl_or_b32 v136, v136, 6, v137
	v_readlane_b32 s0, v253, 30
	s_cselect_b64 s[42:43], -1, 0
	s_mov_b32 s50, 0
	v_lshl_add_u32 v134, v141, 1, v134
	v_mov_b32_e32 v135, v145
	v_lshl_add_u32 v136, v138, 1, v136
	v_mov_b32_e32 v137, v145
	v_add_u32_e32 v151, 0, v151
	s_mov_b32 s52, s0
	v_readlane_b32 s51, v253, 24
	v_readlane_b32 s1, v253, 31
	s_branch .LBB0_1555

; #define PG8_STAGE(bufoff, gbase, voff) do { _Pragma("unroll") for (int _i = 0; _i < 2; ++_i) \
;         __builtin_amdgcn_global_load_lds((const unsigned*)((const char*)(gbase) + (voff)[_i]), (PG8_LAS unsigned*)(lds + (bufoff) + ldsw + _i * 8192), 16, 0, 0); } while (0)
; #define PG8_WAIT_V(n) asm volatile("s_waitcnt vmcnt(" #n ")" ::: "memory")
; #define PG8_BAR __builtin_amdgcn_s_barrier()
; template <class Epi, class Sched, bool ALIGN_EPI = false, bool SP2 = false>
; __device__ __forceinline__ void gemm_phase(PG8_LAS unsigned char* lds, const Gemm g, const Sched& S, const Epi& E) {
;     ...
;     for (int i = 0; i < 2; ++i) { int R, C; stage_rc(tid * 16 + i * 8192, R, C); const int Rb = Epi::PERM ? ((R & ~31) + perm32(R & 31)) : R;
;         voffA[i] = (unsigned)(R * K + C) * 2u; voffB[i] = (unsigned)(Rb * K + C) * 2u; }
;     const size_t kstep = (size_t)(BK * 2);
;     const size_t hstep = (size_t)HALF * K * 2;
;     const size_t tstep = 2 * hstep;
;     const unsigned ldsw = (unsigned)wid * 1024u;
;     const int aoff = lds_byte(wr * 64 + fr, fq * 8), boff = lds_byte(wc * 32 + fr, fq * 8);
;     ...
;         PG8_STAGE(PG8_SB(1, 0), cB + kstep, voffB); PG8_STAGE(PG8_SA(1, 0), cA + kstep, voffA); PG8_STAGE(PG8_SB(1, 1), cB + hstep + kstep, voffB);
;         PG8_WAIT_V(6); PG8_BAR;
.LBB0_1641:
	v_and_b32_e32 v16, 15, v4
	v_lshl_or_b32 v163, s6, 6, v16
	v_readlane_b32 s16, v253, 7
	v_lshlrev_b32_e32 v18, 6, v163
	v_and_b32_e32 v19, 48, v4
	s_movk_i32 s7, 0x3c0
	v_lshlrev_b32_e32 v21, 2, v4
	s_lshl_b32 s35, s5, 5
	v_mov_b32_e32 v155, v145
	v_readlane_b32 s17, v253, 8
	v_and_or_b32 v20, v18, s7, v19
	s_lshl_b32 s6, s6, 13
	v_and_b32_e32 v21, 32, v21
	s_and_b32 s36, s35, 0x60
	s_add_i32 m0, s27, 0x18000
	v_lshl_add_u64 v[0:1], v[0:1], 0, s[94:95]
	v_lshl_add_u64 v[12:13], s[16:17], 0, v[154:155]
	v_mov_b32_e32 v153, v145
	v_bitop3_b32 v20, v20, s6, v21 bitop3:0xde
	v_lshl_or_b32 v16, v16, 6, v19
	s_lshl_b32 s6, s36, 7
	global_load_lds_dwordx4 v[0:1], off
	v_lshl_add_u64 v[0:1], v[2:3], 0, s[94:95]
	s_add_i32 m0, s27, 0x1a000
	s_add_i32 s31, s27, 0x8000
	s_add_i32 s34, s27, 0xa000
	v_lshl_add_u64 v[14:15], s[16:17], 0, v[152:153]
	v_bitop3_b32 v165, s6, v16, v21 bitop3:0xf6
	global_load_lds_dwordx4 v[0:1], off
	v_lshl_add_u64 v[0:1], v[12:13], 0, s[94:95]
	s_mov_b32 m0, s31
	s_add_u32 s6, s0, 0x40080
	global_load_lds_dwordx4 v[0:1], off
	v_lshl_add_u64 v[0:1], v[14:15], 0, s[94:95]
	s_mov_b32 m0, s34
	s_addc_u32 s7, s1, 0
	global_load_lds_dwordx4 v[0:1], off
	s_add_i32 m0, s27, 0x1c000
	v_lshl_add_u64 v[0:1], s[6:7], 0, v[144:145]
	global_load_lds_dwordx4 v[0:1], off
	v_lshl_add_u64 v[0:1], s[6:7], 0, v[150:151]
	s_add_i32 m0, s27, 0x1e000
	v_lshrrev_b32_e32 v17, 1, v4
	global_load_lds_dwordx4 v[0:1], off
	s_waitcnt vmcnt(8)
	s_barrier
	s_waitcnt vmcnt(6)
	s_barrier
	v_lshrrev_b32_e32 v0, 2, v4
	v_and_or_b32 v167, v0, 15, s35
	v_and_b32_e32 v0, 48, v7
	v_mov_b32_e32 v1, v145
	v_lshl_add_u64 v[156:157], s[92:93], 0, v[0:1]
	v_lshlrev_b32_e32 v1, 14, v10
	v_and_b32_e32 v1, 0xffff8000, v1
	v_lshl_add_u32 v1, v9, 11, v1
	v_and_b32_e32 v2, 1, v10
	v_lshl_or_b32 v1, v2, 6, v1
	s_lshl_b32 s5, s5, 11
	v_lshl_add_u32 v158, v11, 1, v1
	v_lshlrev_b32_e32 v1, 14, v5
	s_cmpk_lt_u32 s4, 0x100
	v_readlane_b32 s4, v253, 45
	v_and_b32_e32 v1, 0xffff8000, v1
	s_cselect_b64 s[42:43], -1, 0
	v_add_u32_e32 v0, s4, v19
	v_lshl_add_u32 v1, v6, 11, v1
	v_and_b32_e32 v2, 1, v5
	s_add_i32 s52, s5, 0
	v_readlane_b32 s4, v253, 5
	v_lshl_or_b32 v1, v2, 6, v1
	v_readlane_b32 s5, v253, 6
	v_and_or_b32 v171, v17, 24, s36
	v_mov_b32_e32 v159, v145
	v_lshl_add_u32 v160, v8, 1, v1
	v_mov_b32_e32 v161, v145
	s_mov_b32 s35, 0
	v_add_u32_e32 v197, 0, v20
	v_add_u32_e32 v198, v0, v18
	s_mov_b32 s55, s4
	v_readlane_b32 s38, v253, 1
	s_mov_b64 s[4:5], s[16:17]
	s_branch .LBB0_1644

; #define PG8_STAGE(bufoff, gbase, voff) do { _Pragma("unroll") for (int _i = 0; _i < 2; ++_i) \
;         __builtin_amdgcn_global_load_lds((const unsigned*)((const char*)(gbase) + (voff)[_i]), (PG8_LAS unsigned*)(lds + (bufoff) + ldsw + _i * 8192), 16, 0, 0); } while (0)
; #define PG8_WAIT_V(n) asm volatile("s_waitcnt vmcnt(" #n ")" ::: "memory")
; #define PG8_BAR __builtin_amdgcn_s_barrier()
; template <class Epi, class Sched, bool ALIGN_EPI = false, bool SP2 = false>
; __device__ __forceinline__ void gemm_phase(PG8_LAS unsigned char* lds, const Gemm g, const Sched& S, const Epi& E) {
;     ...
;         PG8_STAGE(PG8_SB(1, 0), cB + kstep, voffB); PG8_STAGE(PG8_SA(1, 0), cA + kstep, voffA); PG8_STAGE(PG8_SB(1, 1), cB + hstep + kstep, voffB);
;         PG8_WAIT_V(6); PG8_BAR;
;     __device__ __forceinline__ void finish(f32x4 (&acc)[2][2][4][2], const Pre& p) const {
; #pragma unroll
;         for (int ai = 0; ai < 2; ++ai)
; #pragma unroll
;             for (int m = 0; m < 4; ++m)
; #pragma unroll
;                 for (int bj = 0; bj < 2; ++bj) { float f[8]; unpack8(p.v[ai][m][bj], f);
;                     acc[ai][bj][m][0] = (f32x4){f[0], f[1], f[2], f[3]} * inv_alpha; acc[ai][bj][m][1] = (f32x4){f[4], f[5], f[6], f[7]} * inv_alpha; }
;     }
.LBB0_1886:
	v_or_b32_e32 v142, s7, v68
	v_lshlrev_b32_e32 v69, 6, v142
	v_lshlrev_b32_e32 v74, 4, v134
	s_movk_i32 s7, 0x3c0
	v_lshlrev_b32_e32 v75, 2, v142
	v_readlane_b32 s16, v253, 32
	v_and_or_b32 v69, v69, s7, v74
	s_lshl_b32 s6, s6, 13
	v_and_b32_e32 v75, 32, v75
	v_mov_b32_e32 v133, v145
	v_readlane_b32 s17, v253, 33
	v_bitop3_b32 v153, v69, s6, v75 bitop3:0xde
	v_lshl_or_b32 v69, v68, 6, v74
	v_lshlrev_b32_e32 v68, 2, v68
	s_add_i32 m0, s30, 0x18000
	v_lshl_add_u64 v[64:65], v[64:65], 0, s[94:95]
	v_lshl_add_u64 v[70:71], s[16:17], 0, v[132:133]
	v_mov_b32_e32 v131, v145
	s_lshl_b32 s6, s28, 12
	v_and_b32_e32 v68, 32, v68
	global_load_lds_dwordx4 v[64:65], off
	v_lshl_add_u64 v[64:65], v[66:67], 0, s[94:95]
	s_add_i32 m0, s30, 0x1a000
	s_add_i32 s50, s30, 0x8000
	s_add_i32 s51, s30, 0xa000
	v_lshl_add_u64 v[72:73], s[16:17], 0, v[130:131]
	v_bitop3_b32 v143, v69, s6, v68 bitop3:0xde
	global_load_lds_dwordx4 v[64:65], off
	v_lshl_add_u64 v[64:65], v[70:71], 0, s[94:95]
	s_mov_b32 m0, s50
	s_add_u32 s6, s4, 0xb0080
	global_load_lds_dwordx4 v[64:65], off
	v_lshl_add_u64 v[64:65], v[72:73], 0, s[94:95]
	s_mov_b32 m0, s51
	s_addc_u32 s7, s5, 0
	global_load_lds_dwordx4 v[64:65], off
	s_add_i32 m0, s30, 0x1c000
	v_lshl_add_u64 v[64:65], s[6:7], 0, v[144:145]
	global_load_lds_dwordx4 v[64:65], off
	v_lshl_add_u64 v[64:65], s[6:7], 0, v[128:129]
	s_add_i32 m0, s30, 0x1e000
	s_nop 0
	global_load_lds_dwordx4 v[64:65], off
	s_waitcnt vmcnt(8)
	s_barrier
	s_waitcnt vmcnt(6)
	s_barrier
	s_waitcnt vmcnt(0)
	v_lshlrev_b32_e32 v124, 16, v60
	v_and_b32_e32 v125, 0xffff0000, v60
	v_lshlrev_b32_e32 v126, 16, v61
	v_and_b32_e32 v127, 0xffff0000, v61
	v_lshlrev_b32_e32 v120, 16, v62
	v_and_b32_e32 v121, 0xffff0000, v62
	v_lshlrev_b32_e32 v122, 16, v63
	v_and_b32_e32 v123, 0xffff0000, v63
	v_lshlrev_b32_e32 v116, 16, v56
	v_and_b32_e32 v117, 0xffff0000, v56
	v_lshlrev_b32_e32 v118, 16, v57
	v_and_b32_e32 v119, 0xffff0000, v57
	v_lshlrev_b32_e32 v112, 16, v58
	v_and_b32_e32 v113, 0xffff0000, v58
	v_lshlrev_b32_e32 v114, 16, v59
	v_and_b32_e32 v115, 0xffff0000, v59
	v_lshlrev_b32_e32 v108, 16, v52
	v_and_b32_e32 v109, 0xffff0000, v52
	v_lshlrev_b32_e32 v110, 16, v53
	v_and_b32_e32 v111, 0xffff0000, v53
	v_lshlrev_b32_e32 v104, 16, v54
	v_and_b32_e32 v105, 0xffff0000, v54
	v_lshlrev_b32_e32 v106, 16, v55
	v_and_b32_e32 v107, 0xffff0000, v55
	v_lshlrev_b32_e32 v100, 16, v48
	v_and_b32_e32 v101, 0xffff0000, v48
	v_lshlrev_b32_e32 v102, 16, v49
	v_and_b32_e32 v103, 0xffff0000, v49
	v_lshlrev_b32_e32 v96, 16, v50
	v_and_b32_e32 v97, 0xffff0000, v50
	v_lshlrev_b32_e32 v98, 16, v51
	v_and_b32_e32 v99, 0xffff0000, v51
	v_lshlrev_b32_e32 v92, 16, v44
	v_and_b32_e32 v93, 0xffff0000, v44
	v_lshlrev_b32_e32 v94, 16, v45
	v_and_b32_e32 v95, 0xffff0000, v45
	v_lshlrev_b32_e32 v88, 16, v46
	v_and_b32_e32 v89, 0xffff0000, v46
	v_lshlrev_b32_e32 v90, 16, v47
	v_and_b32_e32 v91, 0xffff0000, v47
	v_lshlrev_b32_e32 v84, 16, v40
	v_and_b32_e32 v85, 0xffff0000, v40
	v_lshlrev_b32_e32 v86, 16, v41
	v_and_b32_e32 v87, 0xffff0000, v41
	v_lshlrev_b32_e32 v80, 16, v42
	v_and_b32_e32 v81, 0xffff0000, v42
	v_lshlrev_b32_e32 v82, 16, v43
	v_and_b32_e32 v83, 0xffff0000, v43
	v_lshlrev_b32_e32 v76, 16, v36
	v_and_b32_e32 v77, 0xffff0000, v36
	v_lshlrev_b32_e32 v78, 16, v37
	v_and_b32_e32 v79, 0xffff0000, v37
	v_lshlrev_b32_e32 v72, 16, v38
	v_and_b32_e32 v73, 0xffff0000, v38
	v_lshlrev_b32_e32 v74, 16, v39
	v_and_b32_e32 v75, 0xffff0000, v39
	v_lshlrev_b32_e32 v68, 16, v28
	v_and_b32_e32 v69, 0xffff0000, v28
	v_lshlrev_b32_e32 v70, 16, v29
	v_and_b32_e32 v71, 0xffff0000, v29
	v_lshlrev_b32_e32 v64, 16, v30
	v_and_b32_e32 v65, 0xffff0000, v30
	v_lshlrev_b32_e32 v66, 16, v31
	v_and_b32_e32 v67, 0xffff0000, v31
	v_lshlrev_b32_e32 v60, 16, v32
	v_and_b32_e32 v61, 0xffff0000, v32
	v_lshlrev_b32_e32 v62, 16, v33
	v_and_b32_e32 v63, 0xffff0000, v33
	v_lshlrev_b32_e32 v56, 16, v34
	v_and_b32_e32 v57, 0xffff0000, v34
	v_lshlrev_b32_e32 v58, 16, v35
	v_and_b32_e32 v59, 0xffff0000, v35
	v_lshlrev_b32_e32 v52, 16, v20
	v_and_b32_e32 v53, 0xffff0000, v20
	v_lshlrev_b32_e32 v54, 16, v21
	v_and_b32_e32 v55, 0xffff0000, v21
	v_lshlrev_b32_e32 v48, 16, v22
	v_and_b32_e32 v49, 0xffff0000, v22
	v_lshlrev_b32_e32 v50, 16, v23
	v_and_b32_e32 v51, 0xffff0000, v23
	v_lshlrev_b32_e32 v44, 16, v24
	v_and_b32_e32 v45, 0xffff0000, v24
	v_lshlrev_b32_e32 v46, 16, v25
	v_and_b32_e32 v47, 0xffff0000, v25
	v_lshlrev_b32_e32 v40, 16, v26
	v_and_b32_e32 v41, 0xffff0000, v26
	v_lshlrev_b32_e32 v42, 16, v27
	v_and_b32_e32 v43, 0xffff0000, v27
	v_lshlrev_b32_e32 v36, 16, v12
	v_and_b32_e32 v37, 0xffff0000, v12
	v_lshlrev_b32_e32 v38, 16, v13
	v_and_b32_e32 v39, 0xffff0000, v13
	v_lshlrev_b32_e32 v32, 16, v14
	v_and_b32_e32 v33, 0xffff0000, v14
	v_lshlrev_b32_e32 v34, 16, v15
	v_and_b32_e32 v35, 0xffff0000, v15
	v_lshlrev_b32_e32 v28, 16, v16
	v_and_b32_e32 v29, 0xffff0000, v16
	v_lshlrev_b32_e32 v30, 16, v17
	v_and_b32_e32 v31, 0xffff0000, v17
	v_lshlrev_b32_e32 v24, 16, v18
	v_and_b32_e32 v25, 0xffff0000, v18
	v_lshlrev_b32_e32 v26, 16, v19
	v_and_b32_e32 v27, 0xffff0000, v19
	v_lshlrev_b32_e32 v20, 16, v4
	v_and_b32_e32 v21, 0xffff0000, v4
	v_lshlrev_b32_e32 v22, 16, v5
	v_and_b32_e32 v23, 0xffff0000, v5
	v_lshlrev_b32_e32 v16, 16, v6
	v_and_b32_e32 v17, 0xffff0000, v6
	v_lshlrev_b32_e32 v18, 16, v7
	v_and_b32_e32 v19, 0xffff0000, v7
	v_lshlrev_b32_e32 v12, 16, v8
	v_and_b32_e32 v13, 0xffff0000, v8
	v_lshlrev_b32_e32 v14, 16, v9
	v_and_b32_e32 v15, 0xffff0000, v9
	v_lshlrev_b32_e32 v8, 16, v10
	v_and_b32_e32 v9, 0xffff0000, v10
	v_lshlrev_b32_e32 v10, 16, v11
	v_and_b32_e32 v11, 0xffff0000, v11
	v_lshlrev_b32_e32 v4, 16, v0
	v_and_b32_e32 v5, 0xffff0000, v0
	v_lshlrev_b32_e32 v6, 16, v1
	v_and_b32_e32 v7, 0xffff0000, v1
	v_lshlrev_b32_e32 v0, 16, v2
	v_and_b32_e32 v1, 0xffff0000, v2
	v_lshlrev_b32_e32 v2, 16, v3
	v_and_b32_e32 v3, 0xffff0000, v3
	s_movk_i32 s7, 0xb00
	v_cmp_eq_u32_e64 s[36:37], 0, v134
	v_or_b32_e32 v150, s1, v135
	v_lshrrev_b32_e32 v135, 1, v141
	v_mul_lo_u32 v134, v140, s7
	s_mov_b32 s6, 0xb000
	v_lshrrev_b32_e32 v140, 1, v136
	v_mul_lo_u32 v136, v137, s7
	s_cmpk_lt_u32 s0, 0x100
	v_mad_u64_u32 v[134:135], s[0:1], v135, s6, v[134:135]
	v_mad_u64_u32 v[136:137], s[0:1], v140, s6, v[136:137]
	v_or_b32_e32 v134, v134, v151
	v_or_b32_e32 v136, v136, v138
	v_add_lshl_u32 v134, v134, v152, 1
	v_mov_b32_e32 v135, v145
	s_mov_b64 s[18:19], 0xb0080
	v_add_lshl_u32 v136, v136, v139, 1
	v_mov_b32_e32 v137, v145
	v_readlane_b32 s0, v253, 30
	s_cselect_b64 s[46:47], -1, 0
	s_mov_b32 s52, 0
	v_lshl_add_u64 v[134:135], v[134:135], 0, s[18:19]
	v_lshl_add_u64 v[136:137], v[136:137], 0, s[18:19]
	v_add_u32_e32 v151, 0, v153
	s_mov_b32 s56, s0
	v_readlane_b32 s55, v253, 24
	s_mov_b64 s[6:7], s[16:17]
	v_readlane_b32 s1, v253, 31
	s_branch .LBB0_1889
